# static priority raise (s_setprio 2) for the scan's four compute waves over the loader waves on the same SIMDs; on v61
# speedup vs baseline: 1.0029x; 1.0029x over previous
; #define LAS __attribute__((address_space(3)))
; #define U_LOAD(nn) do { const unsigned char* tr_ = P.tr + (size_t)((b << 8) | ((nn) << 3) | h) * TR_SZ; \
;             _Pragma("unroll") for (int mt_ = 0; mt_ < 4; ++mt_) ubn[mt_] = *(const f32x4*)(tr_ + (oU + (unsigned)mt_ * 1024u)); } while (0)
; __device__ __forceinline__ void scan_bh(LAS unsigned char* lds, const ScanP& P, int b, int h, int half, int tid, int lane, int wave) {
;     ...
;         f32x4 S[8];
; #pragma unroll
;         for (int i = 0; i < 8; ++i) S[i] = (f32x4){0.f, 0.f, 0.f, 0.f};
;         const float glv = (lane < 32) ? P.gl[(b << 8) | (lane << 3) | h] : 0.f;
;         f32x4 ubn[4];
;         const unsigned oU = (unsigned)TR_U + (unsigned)(ct * 256 + lane) * 16u;
;     ...
;         U_LOAD(0);
;         __syncthreads();
; #pragma unroll 1
;         for (int n = 0; n < 32; ++n) {
;             LAS unsigned char* buf = lds + (n & 1) * SB_SZ;
;             const LAS bf16_t* Wl = (const LAS bf16_t*)(buf + SB_W); const LAS bf16_t* Ql = (const LAS bf16_t*)(buf + SB_Q);
;             const LAS bf16_t* Al = (const LAS bf16_t*)(buf + SB_A); const LAS bf16_t* Kl = (const LAS bf16_t*)(buf + SB_K);
;             f32x4 u[4], o[4];
; #pragma unroll
;             for (int mt = 0; mt < 4; ++mt) { u[mt] = ubn[mt]; o[mt] = (f32x4){0.f, 0.f, 0.f, 0.f}; }
;             if (n + 1 < 32) U_LOAD(n + 1);
.LBB0_528:
	s_or_b64 exec, exec, s[4:5]
	s_lshr_b32 s4, s10, 1
	s_and_b32 s4, s4, 4
	s_and_b32 s5, s11, 3
	s_or_b32 s7, s5, s4
	v_lshlrev_b32_e32 v6, 4, v5
	s_waitcnt vmcnt(11)
	v_lshl_or_b32 v12, s7, 12, v6
	s_or_b32 s6, s6, s8
	v_add_u32_e32 v68, 0x12000, v12
	v_mad_i64_i32 v[6:7], s[4:5], s6, v199, v[116:117]
	v_mov_b32_e32 v69, v153
	v_add_u32_e32 v70, 0x12400, v12
	v_mov_b32_e32 v71, v153
	v_add_u32_e32 v72, 0x12800, v12
	v_mov_b32_e32 v73, v153
	v_add_u32_e32 v74, 0x12c00, v12
	v_mov_b32_e32 v75, v153
	v_lshl_add_u64 v[8:9], v[6:7], 0, v[68:69]
	v_lshl_add_u64 v[10:11], v[6:7], 0, v[72:73]
	v_lshl_add_u64 v[12:13], v[6:7], 0, v[74:75]
	v_lshl_add_u64 v[6:7], v[6:7], 0, v[70:71]
	global_load_dwordx4 v[56:59], v[10:11], off
	global_load_dwordx4 v[52:55], v[12:13], off
	global_load_dwordx4 v[60:63], v[6:7], off
	global_load_dwordx4 v[64:67], v[8:9], off
	s_add_i32 s15, s6, 8
	v_mad_i64_i32 v[44:45], s[16:17], s15, v199, v[116:117]
	v_lshl_add_u64 v[36:37], v[44:45], 0, v[74:75]
	v_lshl_add_u64 v[38:39], v[44:45], 0, v[72:73]
	v_lshl_add_u64 v[46:47], v[44:45], 0, v[70:71]
	v_lshl_add_u64 v[44:45], v[44:45], 0, v[68:69]
	global_load_dwordx4 v[176:179], v[36:37], off
	global_load_dwordx4 v[180:183], v[38:39], off
	global_load_dwordx4 v[184:187], v[46:47], off
	global_load_dwordx4 v[188:191], v[44:45], off
	s_add_i32 s15, s6, 16
	v_mad_i64_i32 v[44:45], s[16:17], s15, v199, v[116:117]
	v_lshl_add_u64 v[36:37], v[44:45], 0, v[74:75]
	v_lshl_add_u64 v[38:39], v[44:45], 0, v[72:73]
	v_lshl_add_u64 v[46:47], v[44:45], 0, v[70:71]
	v_lshl_add_u64 v[44:45], v[44:45], 0, v[68:69]
	global_load_dwordx4 v[200:203], v[36:37], off
	global_load_dwordx4 v[204:207], v[38:39], off
	global_load_dwordx4 v[208:211], v[46:47], off
	global_load_dwordx4 v[212:215], v[44:45], off
	s_add_i32 s15, s6, 24
	v_mad_i64_i32 v[44:45], s[16:17], s15, v199, v[116:117]
	v_lshl_add_u64 v[36:37], v[44:45], 0, v[74:75]
	v_lshl_add_u64 v[38:39], v[44:45], 0, v[72:73]
	v_lshl_add_u64 v[46:47], v[44:45], 0, v[70:71]
	v_lshl_add_u64 v[44:45], v[44:45], 0, v[68:69]
	global_load_dwordx4 v[216:219], v[36:37], off
	global_load_dwordx4 v[220:223], v[38:39], off
	global_load_dwordx4 v[224:227], v[46:47], off
	global_load_dwordx4 v[228:231], v[44:45], off
	s_lshl_b32 s4, s9, 11
	v_lshrrev_b32_e32 v77, 4, v5
	v_or_b32_e32 v6, 48, v5
	v_or_b32_e32 v5, 0x70, v5
	s_ashr_i32 s5, s4, 31
	s_lshl_b32 s7, s7, 4
	v_mul_u32_u24_e32 v81, 0x90, v5
	v_lshlrev_b32_e32 v5, 12, v77
	s_lshl_b64 s[4:5], s[4:5], 12
	s_lshl_b32 s11, s8, 9
	v_or3_b32 v5, v5, v144, s7
	s_or_b32 s4, s4, s11
	v_mul_u32_u24_e32 v7, 0x48, v144
	v_lshlrev_b32_e32 v8, 3, v77
	v_lshlrev_b32_e32 v82, 2, v5
	v_lshlrev_b32_e32 v5, 7, v6
	v_lshl_add_u64 v[2:3], v[2:3], 0, s[4:5]
	v_mul_u32_u24_e32 v78, 0x110, v144
	v_and_b32_e32 v79, 48, v145
	v_mul_u32_u24_e32 v80, 0x110, v6
	s_mov_b32 s10, 0
	v_sub_u32_e32 v83, 0, v5
	v_lshl_add_u64 v[2:3], v[2:3], 0, s[20:21]
	s_mov_b64 s[4:5], 0
	s_mov_b32 s11, 8
	v_lshlrev_b32_e32 v84, 1, v7
	v_lshlrev_b32_e32 v85, 1, v8
	s_mov_b32 s14, 0
	v_mov_b32_e32 v5, v4
	v_mov_b32_e32 v6, v4
	v_mov_b32_e32 v7, v4
	s_waitcnt vmcnt(11)
	v_mov_b32_e32 v28, v4
	v_mov_b32_e32 v29, v4
	v_mov_b32_e32 v30, v4
	v_mov_b32_e32 v31, v4
	s_waitcnt vmcnt(10)
	v_mov_b32_e32 v32, v4
	v_mov_b32_e32 v33, v4
	v_mov_b32_e32 v34, v4
	v_mov_b32_e32 v35, v4
	v_mov_b32_e32 v12, v4
	v_mov_b32_e32 v13, v4
	v_mov_b32_e32 v14, v4
	v_mov_b32_e32 v15, v4
	v_mov_b32_e32 v20, v4
	v_mov_b32_e32 v21, v4
	v_mov_b32_e32 v22, v4
	v_mov_b32_e32 v23, v4
	v_mov_b32_e32 v8, v4
	v_mov_b32_e32 v9, v4
	v_mov_b32_e32 v10, v4
	v_mov_b32_e32 v11, v4
	v_mov_b32_e32 v24, v4
	v_mov_b32_e32 v25, v4
	v_mov_b32_e32 v26, v4
	v_mov_b32_e32 v27, v4
	v_mov_b32_e32 v16, v4
	v_mov_b32_e32 v17, v4
	v_mov_b32_e32 v18, v4
	v_mov_b32_e32 v19, v4
	s_waitcnt lgkmcnt(0)
	s_barrier
	s_waitcnt vmcnt(0)
	v_add_u32_e32 v236, 0x0, v82
	v_add_u32_e32 v237, 0x1000, v82
	v_add_u32_e32 v238, 0x2000, v82
	v_add_u32_e32 v239, 0x3000, v82
	v_add_u32_e32 v240, 0x10000, v82
	v_add_u32_e32 v241, 0x11000, v82
	v_add_u32_e32 v242, 0x12000, v82
	v_add_u32_e32 v243, 0x13000, v82
	v_add_u32_e32 v244, 0x20000, v82
	v_add_u32_e32 v245, 0x21000, v82
	v_add_u32_e32 v246, 0x22000, v82
	v_add_u32_e32 v247, 0x23000, v82
	v_add_u32_e32 v248, 0x30000, v82
	v_add_u32_e32 v249, 0x31000, v82
	v_add_u32_e32 v250, 0x32000, v82
	v_add_u32_e32 v251, 0x33000, v82
	v_readfirstlane_b32 s24, v2
	v_readfirstlane_b32 s25, v3
	s_setprio 2

; __device__ __forceinline__ void scan_bh(LAS unsigned char* lds, const ScanP& P, int b, int h, int half, int tid, int lane, int wave) {
;     ...
; #pragma unroll
;         for (int dt = 0; dt < 8; ++dt)
; #pragma unroll
;             for (int j = 0; j < 4; ++j) P.sout[(size_t)(dt * 16 + q8 * 4 + j) * HD + c0 + r] = S[dt][j];
.LBB0_532:
	s_setprio 0
	s_lshl_b32 s4, s92, 2
	s_add_i32 s4, s9, s4
	s_ashr_i32 s5, s4, 31
	s_lshl_b64 s[4:5], s[4:5], 19
	v_lshlrev_b32_e32 v2, 9, v77
	v_lshl_add_u64 v[0:1], v[0:1], 0, s[4:5]
	s_lshl_b32 s38, s8, 16
	v_or3_b32 v2, v2, v144, s7
	v_lshl_add_u64 v[0:1], v[0:1], 0, s[38:39]
	v_lshlrev_b32_e32 v152, 2, v2
	v_lshl_add_u64 v[0:1], v[0:1], 0, v[152:153]
	s_mov_b64 s[4:5], 0x41b0000
	v_lshl_add_u64 v[2:3], v[0:1], 0, s[4:5]
	s_mov_b32 s4, 0x41b0000
	v_add_co_u32_e32 v36, vcc, s4, v0
	s_mov_b32 s4, 0x41b2000
	s_nop 0
	v_addc_co_u32_e32 v37, vcc, 0, v1, vcc
	global_store_dword v[36:37], v4, off
	global_store_dword v[2:3], v5, off offset:512
	global_store_dword v[2:3], v6, off offset:1024
	global_store_dword v[2:3], v7, off offset:1536
	v_add_co_u32_e32 v2, vcc, s4, v0
	s_mov_b32 s4, 0x41b4000
	s_nop 0
	v_addc_co_u32_e32 v3, vcc, 0, v1, vcc
	global_store_dword v[2:3], v28, off
	global_store_dword v[2:3], v29, off offset:512
	global_store_dword v[2:3], v30, off offset:1024
	global_store_dword v[2:3], v31, off offset:1536
	v_add_co_u32_e32 v2, vcc, s4, v0
	s_mov_b32 s4, 0x41b6000
	s_nop 0
	v_addc_co_u32_e32 v3, vcc, 0, v1, vcc
	global_store_dword v[2:3], v32, off
	global_store_dword v[2:3], v33, off offset:512
	global_store_dword v[2:3], v34, off offset:1024
	global_store_dword v[2:3], v35, off offset:1536
	v_add_co_u32_e32 v2, vcc, s4, v0
	s_mov_b32 s4, 0x41b8000
	s_nop 0
	v_addc_co_u32_e32 v3, vcc, 0, v1, vcc
	global_store_dword v[2:3], v12, off
	global_store_dword v[2:3], v13, off offset:512
	global_store_dword v[2:3], v14, off offset:1024
	global_store_dword v[2:3], v15, off offset:1536
	v_add_co_u32_e32 v2, vcc, s4, v0
	s_mov_b32 s4, 0x41ba000
	s_nop 0
	v_addc_co_u32_e32 v3, vcc, 0, v1, vcc
	global_store_dword v[2:3], v20, off
	global_store_dword v[2:3], v21, off offset:512
	global_store_dword v[2:3], v22, off offset:1024
	global_store_dword v[2:3], v23, off offset:1536
	v_add_co_u32_e32 v2, vcc, s4, v0
	s_mov_b32 s4, 0x41bc000
	s_nop 0
	v_addc_co_u32_e32 v3, vcc, 0, v1, vcc
	global_store_dword v[2:3], v8, off
	global_store_dword v[2:3], v9, off offset:512
	global_store_dword v[2:3], v10, off offset:1024
	global_store_dword v[2:3], v11, off offset:1536
	v_add_co_u32_e32 v2, vcc, s4, v0
	s_nop 1
	v_addc_co_u32_e32 v3, vcc, 0, v1, vcc
	v_add_co_u32_e32 v0, vcc, 0x41be000, v0
	global_store_dword v[2:3], v24, off
	global_store_dword v[2:3], v25, off offset:512
	global_store_dword v[2:3], v26, off offset:1024
	global_store_dword v[2:3], v27, off offset:1536
	v_addc_co_u32_e32 v1, vcc, 0, v1, vcc
	global_store_dword v[0:1], v16, off
	global_store_dword v[0:1], v17, off offset:512
	global_store_dword v[0:1], v18, off offset:1024
	global_store_dword v[0:1], v19, off offset:1536
